# gemm_in rope epilogue: the fourth rope-table load of each row group issued before the first wait (one round trip per group instead of two)
# speedup vs baseline: 1.0077x; 1.0021x over previous
.LBB0_332:
	v_lshlrev_b32_e32 v50, 6, v52
	v_mov_b32_e32 v51, v0
	v_and_b32_e32 v50, 0x7c0, v50
	global_load_dwordx4 v[54:57], v[102:103], off
	global_load_dwordx4 v[58:61], v[100:101], off
	v_lshl_add_u64 v[62:63], v[70:71], 0, v[50:51]
	v_lshl_add_u64 v[50:51], v[68:69], 0, v[50:51]
	global_load_dwordx4 v[62:65], v[62:63], off
	global_load_dwordx4 v[112:115], v[50:51], off
	s_waitcnt vmcnt(0)
	v_mul_f32_e32 v122, v44, v56
	v_pk_mul_f32 v[50:51], v[46:47], v[54:55]
	v_pk_mul_f32 v[54:55], v[42:43], v[54:55]
	v_mul_f32_e32 v120, v48, v60
	v_mul_f32_e32 v60, v44, v60
	v_mul_f32_e32 v124, v48, v56
	v_mov_b32_e32 v44, v49
	v_mov_b32_e32 v56, v61
	v_mov_b32_e32 v48, v45
	v_pk_mul_f32 v[44:45], v[44:45], v[56:57]
	v_pk_mul_f32 v[48:49], v[48:49], v[56:57]
	v_pk_fma_f32 v[46:47], v[46:47], v[58:59], v[54:55] neg_lo:[0,0,1] neg_hi:[0,0,1]
	v_pk_fma_f32 v[42:43], v[42:43], v[58:59], v[50:51]
	v_pk_mul_f32 v[50:51], v[38:39], v[62:63]
	v_pk_mul_f32 v[54:55], v[34:35], v[62:63]
	v_mul_f32_e32 v58, v36, v64
	v_mov_b32_e32 v121, v44
	v_mov_b32_e32 v123, v45
	v_mov_b32_e32 v61, v48
	v_mov_b32_e32 v125, v49
	v_pk_add_f32 v[48:49], v[120:121], v[122:123] neg_lo:[0,1] neg_hi:[0,1]
	v_pk_add_f32 v[44:45], v[60:61], v[124:125]
	s_waitcnt vmcnt(0)
	v_mul_f32_e32 v56, v40, v114
	v_mul_f32_e32 v62, v36, v114
	v_mul_f32_e32 v114, v40, v64
	v_mov_b32_e32 v36, v41
	v_mov_b32_e32 v64, v115
	v_mov_b32_e32 v40, v37
	v_pk_mul_f32 v[36:37], v[36:37], v[64:65]
	v_pk_mul_f32 v[40:41], v[40:41], v[64:65]
	v_mov_b32_e32 v57, v36
	v_mov_b32_e32 v59, v37
	v_mov_b32_e32 v63, v40
	v_mov_b32_e32 v115, v41
	v_pk_fma_f32 v[38:39], v[38:39], v[112:113], v[54:55] neg_lo:[0,0,1] neg_hi:[0,0,1]
	v_pk_fma_f32 v[34:35], v[34:35], v[112:113], v[50:51]
	v_pk_add_f32 v[40:41], v[56:57], v[58:59] neg_lo:[0,1] neg_hi:[0,1]
	v_pk_add_f32 v[36:37], v[62:63], v[114:115]
	v_mad_i64_i32 v[50:51], s[12:13], v52, s9, v[104:105]
	s_and_saveexec_b64 s[12:13], s[0:1]
	s_cbranch_execz .LBB0_315

.LBB0_337:
	v_lshlrev_b32_e32 v34, 6, v36
	v_mov_b32_e32 v35, v0
	v_and_b32_e32 v34, 0xbc0, v34
	global_load_dwordx4 v[38:41], v[102:103], off
	global_load_dwordx4 v[42:45], v[100:101], off
	v_lshl_add_u64 v[46:47], v[70:71], 0, v[34:35]
	v_lshl_add_u64 v[34:35], v[68:69], 0, v[34:35]
	global_load_dwordx4 v[46:49], v[46:47], off
	global_load_dwordx4 v[50:53], v[34:35], off
	s_waitcnt vmcnt(0)
	v_mul_f32_e32 v56, v28, v40
	v_pk_mul_f32 v[34:35], v[30:31], v[38:39]
	v_pk_mul_f32 v[38:39], v[26:27], v[38:39]
	v_mul_f32_e32 v54, v32, v44
	v_mul_f32_e32 v44, v28, v44
	v_mul_f32_e32 v58, v32, v40
	v_mov_b32_e32 v28, v33
	v_mov_b32_e32 v40, v45
	v_mov_b32_e32 v32, v29
	v_pk_mul_f32 v[28:29], v[28:29], v[40:41]
	v_pk_mul_f32 v[32:33], v[32:33], v[40:41]
	v_pk_fma_f32 v[30:31], v[30:31], v[42:43], v[38:39] neg_lo:[0,0,1] neg_hi:[0,0,1]
	v_pk_fma_f32 v[26:27], v[26:27], v[42:43], v[34:35]
	v_pk_mul_f32 v[34:35], v[22:23], v[46:47]
	v_pk_mul_f32 v[38:39], v[18:19], v[46:47]
	v_mul_f32_e32 v42, v20, v48
	v_mov_b32_e32 v55, v28
	v_mov_b32_e32 v57, v29
	v_mov_b32_e32 v45, v32
	v_mov_b32_e32 v59, v33
	v_pk_add_f32 v[32:33], v[54:55], v[56:57] neg_lo:[0,1] neg_hi:[0,1]
	v_pk_add_f32 v[28:29], v[44:45], v[58:59]
	s_waitcnt vmcnt(0)
	v_mul_f32_e32 v40, v24, v52
	v_mul_f32_e32 v46, v20, v52
	v_mul_f32_e32 v52, v24, v48
	v_mov_b32_e32 v20, v25
	v_mov_b32_e32 v48, v53
	v_mov_b32_e32 v24, v21
	v_pk_mul_f32 v[20:21], v[20:21], v[48:49]
	v_pk_mul_f32 v[24:25], v[24:25], v[48:49]
	v_mov_b32_e32 v41, v20
	v_mov_b32_e32 v43, v21
	v_mov_b32_e32 v47, v24
	v_mov_b32_e32 v53, v25
	v_pk_fma_f32 v[22:23], v[22:23], v[50:51], v[38:39] neg_lo:[0,0,1] neg_hi:[0,0,1]
	v_pk_fma_f32 v[18:19], v[18:19], v[50:51], v[34:35]
	v_pk_add_f32 v[24:25], v[40:41], v[42:43] neg_lo:[0,1] neg_hi:[0,1]
	v_pk_add_f32 v[20:21], v[46:47], v[52:53]
	v_mad_i64_i32 v[34:35], s[12:13], v36, s9, v[104:105]
	s_and_saveexec_b64 s[12:13], s[0:1]
	s_cbranch_execz .LBB0_322

.LBB0_343:
	v_lshlrev_b32_e32 v18, 6, v20
	v_mov_b32_e32 v19, v0
	v_and_b32_e32 v18, 0xfc0, v18
	global_load_dwordx4 v[22:25], v[102:103], off
	global_load_dwordx4 v[26:29], v[100:101], off
	v_lshl_add_u64 v[30:31], v[70:71], 0, v[18:19]
	v_lshl_add_u64 v[18:19], v[68:69], 0, v[18:19]
	global_load_dwordx4 v[30:33], v[30:31], off
	global_load_dwordx4 v[34:37], v[18:19], off
	s_waitcnt vmcnt(0)
	v_mul_f32_e32 v40, v8, v24
	v_pk_mul_f32 v[18:19], v[10:11], v[22:23]
	v_pk_mul_f32 v[22:23], v[6:7], v[22:23]
	v_mul_f32_e32 v38, v12, v28
	v_mul_f32_e32 v28, v8, v28
	v_mul_f32_e32 v42, v12, v24
	v_mov_b32_e32 v8, v13
	v_mov_b32_e32 v24, v29
	v_mov_b32_e32 v12, v9
	v_pk_mul_f32 v[8:9], v[8:9], v[24:25]
	v_pk_mul_f32 v[12:13], v[12:13], v[24:25]
	v_pk_fma_f32 v[10:11], v[10:11], v[26:27], v[22:23] neg_lo:[0,0,1] neg_hi:[0,0,1]
	v_pk_fma_f32 v[6:7], v[6:7], v[26:27], v[18:19]
	v_pk_mul_f32 v[18:19], v[2:3], v[30:31]
	v_pk_mul_f32 v[22:23], v[14:15], v[30:31]
	v_mul_f32_e32 v26, v16, v32
	v_mov_b32_e32 v39, v8
	v_mov_b32_e32 v41, v9
	v_mov_b32_e32 v29, v12
	v_mov_b32_e32 v43, v13
	v_pk_add_f32 v[12:13], v[38:39], v[40:41] neg_lo:[0,1] neg_hi:[0,1]
	v_pk_add_f32 v[8:9], v[28:29], v[42:43]
	s_waitcnt vmcnt(0)
	v_mul_f32_e32 v24, v4, v36
	v_mul_f32_e32 v30, v16, v36
	v_mul_f32_e32 v36, v4, v32
	v_mov_b32_e32 v16, v5
	v_mov_b32_e32 v32, v37
	v_mov_b32_e32 v4, v17
	v_pk_mul_f32 v[16:17], v[16:17], v[32:33]
	v_pk_mul_f32 v[4:5], v[4:5], v[32:33]
	v_mov_b32_e32 v25, v16
	v_mov_b32_e32 v27, v17
	v_mov_b32_e32 v31, v4
	v_mov_b32_e32 v37, v5
	v_pk_fma_f32 v[2:3], v[2:3], v[34:35], v[22:23] neg_lo:[0,0,1] neg_hi:[0,0,1]
	v_pk_fma_f32 v[14:15], v[14:15], v[34:35], v[18:19]
	v_pk_add_f32 v[4:5], v[24:25], v[26:27] neg_lo:[0,1] neg_hi:[0,1]
	v_pk_add_f32 v[16:17], v[30:31], v[36:37]
	v_mad_i64_i32 v[18:19], s[12:13], v20, s9, v[104:105]
	s_and_saveexec_b64 s[12:13], s[0:1]
	s_cbranch_execz .LBB0_328
